# c6 + GDN gate softplus: log1p(e) via f32 hardware log with Kahan correction log(u)*e/(u-1) instead of the double-float library sequence (f32 math, same kind)
# speedup vs baseline: 1.0040x; 1.0040x over previous
.LBB0_355:
	s_waitcnt vmcnt(0)
	v_lshlrev_b32_e32 v0, 16, v186
	v_add_f32_e32 v0, v203, v0
	v_mov_b32_e32 v205, v174
	v_cmp_nlt_f32_e32 vcc, s66, v0
	s_and_saveexec_b64 s[10:11], vcc
	s_cbranch_execz .LBB0_357
	v_mul_f32_e32 v0, 0x3fb8aa3b, v0
	v_exp_f32_e32 v0, v0
	s_nop 0
	v_add_f32_e32 v3, 1.0, v0
	v_add_f32_e32 v108, -1.0, v3
	v_log_f32_e32 v109, v3
	v_rcp_f32_e32 v110, v108
	v_cmp_neq_f32_e32 vcc, 1.0, v3
	v_mul_f32_e32 v109, 0x3f317218, v109
	v_mul_f32_e32 v110, v0, v110
	v_mul_f32_e32 v109, v109, v110
	v_cndmask_b32_e32 v0, v0, v109, vcc
